# work-queue index of the next item requested one item ahead in M1 and M2 (atomic round trip overlaps the item)
# baseline (speedup 1.0000x reference)
.LBB0_549:
	s_or_b64 exec, exec, s[4:5]
	s_lshl_b32 s68, s52, 1
	s_lshl_b64 s[6:7], s[68:69], 2
	s_waitcnt lgkmcnt(0)
	s_barrier
	s_add_u32 s4, s66, s6
	v_writelane_b32 v249, s6, 4
	s_addc_u32 s5, s67, s7
	v_cmp_eq_u32_e64 s[8:9], 0, v203
	v_writelane_b32 v249, s7, 5
	s_add_u32 s6, s4, 0x100000
	s_addc_u32 s7, s5, 0
	s_add_u32 s4, s66, 0x38f8400
	v_writelane_b32 v249, s4, 6
	s_addc_u32 s4, s67, 0
	v_writelane_b32 v249, s4, 8
	s_lshl_b32 s4, s52, 10
	s_mov_b32 s5, s69
	v_writelane_b32 v249, s4, 9
	s_mul_i32 s16, s52, 0x300
	s_mov_b32 s17, s69
	v_writelane_b32 v249, s5, 10
	s_add_u32 s4, s66, 0x2df8400
	v_writelane_b32 v249, s4, 11
	s_addc_u32 s4, s67, 0
	v_writelane_b32 v249, s4, 13
	s_lshl_b32 s4, s52, 22
	v_writelane_b32 v249, s4, 15
	s_add_u32 s4, s66, 0x2bf8400
	v_writelane_b32 v249, s4, 17
	s_addc_u32 s4, s67, 0
	v_writelane_b32 v249, s4, 19
	s_lshl_b32 s4, s52, 20
	v_writelane_b32 v249, s4, 21
	s_add_u32 s4, s66, 0x2b78400
	v_writelane_b32 v249, s4, 23
	s_addc_u32 s4, s67, 0
	v_writelane_b32 v249, s4, 25
	s_add_u32 s4, s66, 0x29f8400
	v_writelane_b32 v249, s4, 27
	s_addc_u32 s4, s67, 0
	v_writelane_b32 v249, s4, 28
	s_add_u32 s4, s66, 0x2878400
	v_writelane_b32 v249, s4, 30
	s_addc_u32 s4, s67, 0
	s_add_u32 s14, s66, 0xea78400
	s_addc_u32 s15, s67, 0
	v_writelane_b32 v249, s4, 31
	s_add_u32 s4, s66, 0x2608400
	v_writelane_b32 v249, s4, 32
	s_addc_u32 s4, s67, 0
	v_writelane_b32 v249, s4, 33
	s_add_u32 s4, s66, 0x1c8400
	s_addc_u32 s5, s67, 0
	v_writelane_b32 v249, s4, 34
	s_nop 1
	v_writelane_b32 v249, s5, 35
	s_add_u32 s4, s66, 0x288400
	s_addc_u32 s5, s67, 0
	v_writelane_b32 v249, s4, 36
	s_nop 1
	v_writelane_b32 v249, s5, 37
	s_add_u32 s4, s66, 0x7678400
	s_addc_u32 s5, s67, 0
	v_writelane_b32 v249, s4, 38
	s_nop 1
	v_writelane_b32 v249, s5, 39
	s_add_u32 s4, s66, 0x8e78400
	s_addc_u32 s5, s67, 0
	s_add_u32 s61, s66, 0x408400
	s_addc_u32 s78, s67, 0
	s_add_u32 s79, s66, 0x100400
	v_writelane_b32 v249, s4, 40
	s_addc_u32 s86, s67, 0
	s_nop 0
	v_writelane_b32 v249, s5, 41
	s_add_u32 s4, s66, 0x3a8400
	v_writelane_b32 v249, s4, 42
	s_addc_u32 s4, s67, 0
	s_add_u32 s89, s66, 0x348400
	s_addc_u32 s90, s67, 0
	v_writelane_b32 v249, s4, 43
	s_and_saveexec_b64 s[26:27], s[8:9]
	s_cbranch_execz .Lq1_first
	v_mov_b32_e32 v251, 1
	global_atomic_add v251, v1, v251, s[6:7] sc0
.Lq1_first:
	s_or_b64 exec, exec, s[26:27]
	s_branch .LBB0_553

.LBB0_553:
	s_barrier
	s_and_saveexec_b64 s[10:11], s[8:9]
	s_cbranch_execz .LBB0_557
	s_waitcnt vmcnt(0)
	v_mov_b32_e32 v2, s71
	ds_write_b32 v2, v251
.LBB0_557:
	s_or_b64 exec, exec, s[10:11]
	v_mov_b32_e32 v0, s71
	s_waitcnt lgkmcnt(0)
	s_barrier
	ds_read_b32 v0, v0
	s_movk_i32 s4, 0xa7f
	s_mov_b64 s[10:11], -1
	s_waitcnt lgkmcnt(0)
	v_cmp_lt_i32_e32 vcc, s4, v0
	v_readfirstlane_b32 s91, v0
	s_cbranch_vccnz .LBB0_552
	s_and_saveexec_b64 s[26:27], s[8:9]
	s_cbranch_execz .Lq1_nopf
	v_mov_b32_e32 v251, 1
	global_atomic_add v251, v1, v251, s[6:7] sc0
.Lq1_nopf:
	s_or_b64 exec, exec, s[26:27]
	s_cmpk_gt_i32 s91, 0xbf
	s_cbranch_scc0 .LBB0_790
	s_cmpk_gt_u32 s91, 0x1bf
	s_cbranch_scc0 .LBB0_656
	s_cmpk_gt_u32 s91, 0x7bf
	s_cbranch_scc0 .LBB0_643
	v_mov_b32_e32 v8, v203
	s_lshl_b32 s5, s91, 3
	v_readfirstlane_b32 s4, v8
	s_ashr_i32 s4, s4, 6
	s_add_i32 s31, s5, s4
	s_addk_i32 s31, 0xc200
	s_cmpk_gt_i32 s31, 0x15ff
	s_cbranch_scc1 .LBB0_642
	s_mulk_i32 s4, 0x2100
	s_add_i32 s30, s4, 0
	v_and_b32_e32 v10, 63, v8
	s_cmpk_gt_i32 s31, 0x17f
	s_cbranch_scc0 .LBB0_616
	s_cmpk_gt_u32 s31, 0x2ff
	s_cbranch_scc0 .LBB0_613
	s_cmpk_gt_u32 s31, 0x37f
	s_cbranch_scc0 .LBB0_610
	s_cmpk_gt_u32 s31, 0x57f
	s_cbranch_scc0 .LBB0_607
	s_cmpk_gt_u32 s31, 0xaff
	s_cbranch_scc0 .LBB0_588
	s_cmpk_gt_u32 s31, 0x107f
	s_cbranch_scc0 .LBB0_569
	s_movk_i32 s4, 0xd8
	v_readlane_b32 s10, v250, 57
	v_readlane_b32 s11, v250, 58
	s_load_dwordx2 s[4:5], s[10:11], s4 offset:0x0
	s_mul_i32 s10, s52, 0xb00000
	v_and_b32_e32 v3, 7, v8
	v_lshlrev_b32_e32 v2, 4, v3
	v_lshrrev_b32_e32 v9, 3, v10
	s_waitcnt lgkmcnt(0)
	s_add_u32 s10, s4, s10
	s_addc_u32 s11, s5, 0
	s_lshl_b32 s4, s31, 1
	s_add_i32 s4, s4, 0x1df00
	s_and_b32 s5, s4, 0x1ffc0
	s_lshl_b32 s4, s31, 5
	s_and_b32 s4, s4, 0x3e0
	v_lshl_or_b32 v0, s4, 2, v2
	v_lshl_add_u64 v[12:13], s[10:11], 0, v[0:1]
	v_or_b32_e32 v0, s5, v9
	v_lshlrev_b32_e32 v0, 12, v0
	v_lshl_add_u64 v[4:5], v[12:13], 0, v[0:1]
	v_mov_b32_e32 v68, 0x8000
	v_mov_b32_e32 v69, 0
	v_lshl_add_u64 v[70:71], v[4:5], 0, v[68:69]
	global_load_dwordx4 v[40:43], v[70:71], off
	v_lshl_add_u64 v[70:71], v[70:71], 0, v[68:69]
	global_load_dwordx4 v[44:47], v[70:71], off
	v_lshl_add_u64 v[70:71], v[70:71], 0, v[68:69]
	global_load_dwordx4 v[48:51], v[70:71], off
	v_lshl_add_u64 v[70:71], v[70:71], 0, v[68:69]
	global_load_dwordx4 v[52:55], v[70:71], off
	v_lshl_add_u64 v[70:71], v[70:71], 0, v[68:69]
	global_load_dwordx4 v[56:59], v[70:71], off
	v_lshl_add_u64 v[70:71], v[70:71], 0, v[68:69]
	global_load_dwordx4 v[60:63], v[70:71], off
	v_lshl_add_u64 v[70:71], v[70:71], 0, v[68:69]
	global_load_dwordx4 v[64:67], v[70:71], off
	global_load_dwordx4 v[4:7], v[4:5], off
	v_mul_u32_u24_e32 v11, 0x84, v9
	v_add3_u32 v11, s30, v2, v11
	v_or_b32_e32 v30, 8, v9
	v_add_u32_e32 v14, 0x420, v11
	v_or_b32_e32 v31, 16, v9
	v_or_b32_e32 v32, 24, v9
	v_readlane_b32 s10, v249, 6
	s_waitcnt vmcnt(0)
	ds_write2_b32 v11, v4, v5 offset1:1
	ds_write2_b32 v11, v6, v7 offset0:2 offset1:3
	v_or_b32_e32 v4, s5, v30
	v_lshlrev_b32_e32 v4, 12, v4
	v_mov_b32_e32 v5, v1
	v_lshl_add_u64 v[4:5], v[12:13], 0, v[4:5]
	v_mov_b64_e32 v[4:5], v[40:41]
	v_mov_b64_e32 v[6:7], v[42:43]
	s_waitcnt vmcnt(0)
	ds_write2_b32 v14, v4, v5 offset1:1
	v_add_u32_e32 v4, 0x428, v11
	ds_write2_b32 v4, v6, v7 offset1:1
	v_or_b32_e32 v4, s5, v31
	v_lshlrev_b32_e32 v4, 12, v4
	v_mov_b32_e32 v5, v1
	v_lshl_add_u64 v[4:5], v[12:13], 0, v[4:5]
	v_mov_b64_e32 v[4:5], v[44:45]
	v_mov_b64_e32 v[6:7], v[46:47]
	v_add_u32_e32 v14, 0x840, v11
	s_waitcnt vmcnt(0)
	ds_write2_b32 v14, v4, v5 offset1:1
	v_add_u32_e32 v4, 0x848, v11
	ds_write2_b32 v4, v6, v7 offset1:1
	v_or_b32_e32 v4, s5, v32
	v_lshlrev_b32_e32 v4, 12, v4
	v_mov_b32_e32 v5, v1
	v_lshl_add_u64 v[4:5], v[12:13], 0, v[4:5]
	v_mov_b64_e32 v[4:5], v[48:49]
	v_mov_b64_e32 v[6:7], v[50:51]
	v_add_u32_e32 v14, 0xc60, v11
	s_lshl_b32 s5, s5, 1
	s_add_u32 s10, s10, s5
	v_readlane_b32 s5, v249, 8
	s_addc_u32 s11, s5, 0
	s_waitcnt vmcnt(0)
	ds_write2_b32 v14, v4, v5 offset1:1
	v_add_u32_e32 v4, 0xc68, v11
	ds_write2_b32 v4, v6, v7 offset1:1
	v_or_b32_e32 v4, 0x20000, v0
	v_mov_b32_e32 v5, v1
	v_lshl_add_u64 v[4:5], v[12:13], 0, v[4:5]
	v_mov_b64_e32 v[4:5], v[52:53]
	v_mov_b64_e32 v[6:7], v[54:55]
	v_add_u32_e32 v14, 0x1080, v11
	s_waitcnt vmcnt(0)
	ds_write2_b32 v14, v4, v5 offset1:1
	v_add_u32_e32 v4, 0x1088, v11
	ds_write2_b32 v4, v6, v7 offset1:1
	v_or_b32_e32 v4, 0x28000, v0
	v_mov_b32_e32 v5, v1
	v_lshl_add_u64 v[4:5], v[12:13], 0, v[4:5]
	v_mov_b64_e32 v[4:5], v[56:57]
	v_mov_b64_e32 v[6:7], v[58:59]
	v_add_u32_e32 v14, 0x14a0, v11
	s_waitcnt vmcnt(0)
	ds_write2_b32 v14, v4, v5 offset1:1
	v_add_u32_e32 v4, 0x14a8, v11
	ds_write2_b32 v4, v6, v7 offset1:1
	v_or_b32_e32 v4, 0x30000, v0
	v_mov_b32_e32 v5, v1
	v_lshl_add_u64 v[4:5], v[12:13], 0, v[4:5]
	v_mov_b64_e32 v[4:5], v[60:61]
	v_mov_b64_e32 v[6:7], v[62:63]
	v_add_u32_e32 v14, 0x18c0, v11
	v_or_b32_e32 v0, 0x38000, v0
	s_waitcnt vmcnt(0)
	ds_write2_b32 v14, v4, v5 offset1:1
	v_add_u32_e32 v4, 0x18c8, v11
	ds_write2_b32 v4, v6, v7 offset1:1
	v_lshl_add_u64 v[4:5], v[12:13], 0, v[0:1]
	v_mov_b64_e32 v[4:5], v[64:65]
	v_mov_b64_e32 v[6:7], v[66:67]
	v_add_u32_e32 v0, 0x1ce0, v11
	s_waitcnt vmcnt(0)
	ds_write2_b32 v0, v4, v5 offset1:1
	v_add_u32_e32 v0, 0x1ce8, v11
	ds_write2_b32 v0, v6, v7 offset1:1
	v_mul_u32_u24_e32 v0, 0x420, v3
	v_lshlrev_b32_e32 v4, 2, v9
	s_waitcnt lgkmcnt(0)
	v_or_b32_e32 v11, s4, v9
	v_add3_u32 v9, s30, v0, v4
	ds_read2_b32 v[12:13], v9 offset0:198 offset1:206
	ds_read2_b32 v[14:15], v9 offset0:231 offset1:239
	ds_read2_b32 v[16:17], v9 offset0:132 offset1:140
	ds_read2_b32 v[18:19], v9 offset0:165 offset1:173
	ds_read2_b32 v[20:21], v9 offset0:66 offset1:74
	ds_read2_b32 v[22:23], v9 offset0:99 offset1:107
	ds_read2_b32 v[24:25], v9 offset0:33 offset1:41
	ds_read2_b32 v[26:27], v9 offset1:8
	v_mov_b32_e32 v3, v1
	v_mul_u32_u24_e32 v0, 0xb00, v11
	v_lshl_add_u64 v[2:3], s[10:11], 0, v[2:3]
	v_lshlrev_b32_e32 v0, 1, v0
	v_lshl_add_u64 v[28:29], v[2:3], 0, v[0:1]
	v_or_b32_e32 v0, s4, v30
	v_mul_u32_u24_e32 v0, 0xb00, v0
	s_waitcnt lgkmcnt(6)
	v_cvt_pk_bf16_f32 v7, v12, v14
	s_waitcnt lgkmcnt(4)
	v_cvt_pk_bf16_f32 v6, v16, v18
	s_waitcnt lgkmcnt(2)
	v_cvt_pk_bf16_f32 v5, v20, v22
	s_waitcnt lgkmcnt(0)
	v_cvt_pk_bf16_f32 v4, v26, v24
	v_lshlrev_b32_e32 v0, 1, v0
	global_store_dwordx4 v[28:29], v[4:7], off
	s_mov_b64 s[10:11], 0
	s_nop 0
	v_cvt_pk_bf16_f32 v7, v13, v15
	v_cvt_pk_bf16_f32 v6, v17, v19
	v_cvt_pk_bf16_f32 v5, v21, v23
	v_cvt_pk_bf16_f32 v4, v27, v25
	v_lshl_add_u64 v[12:13], v[2:3], 0, v[0:1]
	global_store_dwordx4 v[12:13], v[4:7], off
	v_or_b32_e32 v0, s4, v31
	ds_read2_b32 v[12:13], v9 offset0:214 offset1:222
	ds_read2_b32 v[14:15], v9 offset0:247 offset1:255
	ds_read2_b32 v[16:17], v9 offset0:148 offset1:156
	ds_read2_b32 v[18:19], v9 offset0:181 offset1:189
	ds_read2_b32 v[20:21], v9 offset0:82 offset1:90
	ds_read2_b32 v[22:23], v9 offset0:115 offset1:123
	ds_read2_b32 v[24:25], v9 offset0:16 offset1:24
	ds_read2_b32 v[26:27], v9 offset0:49 offset1:57
	v_mul_u32_u24_e32 v0, 0xb00, v0
	v_lshlrev_b32_e32 v0, 1, v0
	v_lshl_add_u64 v[28:29], v[2:3], 0, v[0:1]
	v_or_b32_e32 v0, s4, v32
	v_mul_u32_u24_e32 v0, 0xb00, v0
	s_waitcnt lgkmcnt(6)
	v_cvt_pk_bf16_f32 v7, v12, v14
	s_waitcnt lgkmcnt(4)
	v_cvt_pk_bf16_f32 v6, v16, v18
	s_waitcnt lgkmcnt(2)
	v_cvt_pk_bf16_f32 v5, v20, v22
	s_waitcnt lgkmcnt(0)
	v_cvt_pk_bf16_f32 v4, v24, v26
	v_lshlrev_b32_e32 v0, 1, v0
	global_store_dwordx4 v[28:29], v[4:7], off
	v_lshl_add_u64 v[2:3], v[2:3], 0, v[0:1]
	s_nop 0
	v_cvt_pk_bf16_f32 v7, v13, v15
	v_cvt_pk_bf16_f32 v6, v17, v19
	v_cvt_pk_bf16_f32 v5, v21, v23
	v_cvt_pk_bf16_f32 v4, v25, v27
	global_store_dwordx4 v[2:3], v[4:7], off
	s_waitcnt lgkmcnt(0)

.LBB0_854:
	s_or_b64 exec, exec, s[6:7]
	s_add_i32 s6, s52, 1
	s_cmp_eq_u32 s52, 3
	s_movk_i32 s4, 0x960
	s_cselect_b32 s22, s4, 0xdfb
	v_readlane_b32 s4, v249, 4
	s_waitcnt lgkmcnt(0)
	s_barrier
	v_readlane_b32 s5, v249, 5
	s_add_u32 s4, s66, s4
	s_addc_u32 s5, s67, s5
	s_add_u32 s20, s4, 0x100004
	s_addc_u32 s21, s5, 0
	s_add_u32 s4, s66, 0x100400
	s_addc_u32 s5, s67, 0
	v_writelane_b32 v249, s4, 44
	s_lshl_b32 s17, s6, 16
	v_bfe_u32 v2, v203, 4, 2
	v_writelane_b32 v249, s5, 45
	s_add_u32 s4, s66, 0x2870400
	v_writelane_b32 v249, s4, 46
	s_addc_u32 s4, s67, 0
	v_writelane_b32 v249, s4, 47
	s_add_u32 s4, s66, 0x2868400
	v_writelane_b32 v249, s4, 48
	s_addc_u32 s4, s67, 0
	v_writelane_b32 v249, s4, 49
	s_lshl_b32 s4, s6, 21
	v_writelane_b32 v249, s4, 50
	s_add_u32 s4, s66, 0x2768400
	v_writelane_b32 v249, s4, 51
	s_addc_u32 s4, s67, 0
	v_writelane_b32 v249, s4, 52
	s_add_u32 s4, s66, 0x2668400
	v_writelane_b32 v249, s4, 53
	s_addc_u32 s4, s67, 0
	v_writelane_b32 v249, s4, 54
	s_mul_i32 s4, s6, 0x60000
	v_writelane_b32 v249, s4, 55
	s_add_u32 s4, s66, 0x2608400
	v_writelane_b32 v249, s4, 56
	s_addc_u32 s4, s67, 0
	v_writelane_b32 v249, s4, 57
	s_add_u32 s4, s66, 0x408400
	v_writelane_b32 v249, s4, 58
	s_addc_u32 s4, s67, 0
	v_writelane_b32 v249, s4, 59
	s_lshl_b32 s4, s6, 10
	s_mov_b32 s5, s69
	v_writelane_b32 v249, s4, 60
	v_ashrrev_i32_e32 v0, 6, v203
	v_and_b32_e32 v205, 15, v203
	v_writelane_b32 v249, s5, 61
	s_add_u32 s4, s66, 0x1488400
	v_writelane_b32 v249, s4, 62
	s_addc_u32 s4, s67, 0
	v_writelane_b32 v249, s4, 63
	s_mul_i32 s4, s6, 0xb00000
	v_writelane_b32 v248, s4, 0
	s_add_u32 s4, s66, 0xf08400
	v_writelane_b32 v248, s4, 1
	s_addc_u32 s4, s67, 0
	v_lshlrev_b32_e32 v160, 2, v2
	v_writelane_b32 v248, s4, 2
	v_add_u32_e32 v204, 0xffffe500, v0
	v_lshlrev_b32_e32 v0, 3, v2
	v_sub_u32_e32 v2, v160, v205
	s_movk_i32 s4, 0x81
	v_writelane_b32 v249, s6, 8
	v_cmp_gt_u32_e64 s[6:7], s4, v2
	v_add_u32_e32 v4, 1, v2
	s_add_u32 s88, s66, 0xea78400
	v_writelane_b32 v249, s6, 28
	s_addc_u32 s89, s67, 0
	v_and_b32_e32 v3, 63, v203
	v_writelane_b32 v249, s7, 29
	v_cmp_gt_u32_e64 s[6:7], s4, v4
	v_add_u32_e32 v4, 2, v2
	v_or_b32_e32 v206, 0xffffff90, v205
	v_writelane_b32 v249, s6, 21
	v_or_b32_e32 v207, 0xffffffb0, v205
	v_or_b32_e32 v208, 0xffffffd0, v205
	v_writelane_b32 v249, s7, 22
	v_cmp_gt_u32_e64 s[6:7], s4, v4
	v_add_u32_e32 v4, 3, v2
	v_or_b32_e32 v209, -16, v203
	v_writelane_b32 v249, s6, 23
	v_or_b32_e32 v210, 16, v160
	v_lshlrev_b32_e32 v162, 1, v0
	v_writelane_b32 v249, s7, 24
	v_cmp_gt_u32_e64 s[6:7], s4, v4
	v_add_u32_e32 v4, 0x80, v2
	s_nop 0
	v_writelane_b32 v249, s6, 25
	s_nop 1
	v_writelane_b32 v249, s7, 26
	v_cmp_gt_u32_e64 s[6:7], s4, v4
	v_add_u32_e32 v4, 0x82, v2
	s_nop 0
	v_writelane_b32 v249, s6, 15
	s_nop 1
	v_writelane_b32 v249, s7, 16
	v_cmp_lt_u32_e64 s[6:7], 12, v2
	v_add_u32_e32 v2, 0x83, v2
	s_nop 0
	v_writelane_b32 v249, s6, 17
	s_nop 1
	v_writelane_b32 v249, s7, 18
	v_cmp_gt_u32_e64 s[6:7], s4, v4
	v_cmp_gt_u32_e64 s[4:5], s4, v2
	v_lshlrev_b32_e32 v2, 14, v205
	v_writelane_b32 v249, s6, 19
	v_lshlrev_b32_e32 v164, 1, v2
	s_nop 0
	v_writelane_b32 v249, s7, 20
	v_writelane_b32 v249, s4, 9
	s_nop 1
	v_writelane_b32 v249, s5, 10
	s_add_u32 s4, s66, 0xd278400
	s_addc_u32 s5, s67, 0
	v_writelane_b32 v249, s4, 11
	s_nop 1
	v_writelane_b32 v249, s5, 12
	v_cmp_gt_u32_e64 s[4:5], 16, v3
	s_nop 1
	v_writelane_b32 v249, s4, 13
	s_nop 1
	v_writelane_b32 v249, s5, 14
	s_add_u32 s4, s66, 0x108400
	s_addc_u32 s5, s67, 0
	v_writelane_b32 v248, s4, 3
	s_nop 1
	v_writelane_b32 v248, s5, 4
	s_add_u32 s4, s66, 0x3a8400
	v_writelane_b32 v249, s4, 42
	s_addc_u32 s4, s67, 0
	v_writelane_b32 v249, s4, 43
	s_add_u32 s4, s66, 0x348400
	v_writelane_b32 v249, s4, 32
	s_addc_u32 s4, s67, 0
	s_add_u32 s18, s66, 0xa678400
	s_addc_u32 s19, s67, 0
	v_writelane_b32 v249, s4, 33
	s_add_u32 s4, s66, 0xea7c300
	v_writelane_b32 v249, s4, 38
	s_addc_u32 s4, s67, 0
	v_writelane_b32 v249, s4, 40
	s_add_u32 s4, s66, 0xc678400
	v_writelane_b32 v249, s4, 4
	s_addc_u32 s4, s67, 0
	v_writelane_b32 v249, s4, 34
	s_add_u32 s4, s66, 0xea7c600
	v_writelane_b32 v249, s4, 36
	s_addc_u32 s4, s67, 0
	v_writelane_b32 v249, s4, 30
	s_add_u32 s4, s66, 0xcc78400
	v_writelane_b32 v249, s4, 31
	s_addc_u32 s4, s67, 0
	s_add_u32 s86, s66, 0x7678400
	s_addc_u32 s87, s67, 0
	v_writelane_b32 v249, s4, 27
	s_add_u32 s4, s66, 0x8e78400
	s_addc_u32 s5, s67, 0
	s_add_u32 s90, s66, 0x5e78400
	s_addc_u32 s91, s67, 0
	s_add_u32 s6, s66, 0x25da400
	s_addc_u32 s7, s67, 0
	v_writelane_b32 v248, s6, 5
	s_nop 1
	v_writelane_b32 v248, s7, 6
	s_add_u32 s6, s66, 0x288400
	s_addc_u32 s7, s67, 0
	s_add_u32 s15, s66, 0x1c8400
	v_writelane_b32 v249, s6, 6
	s_addc_u32 s23, s67, 0
	s_nop 0
	v_writelane_b32 v249, s7, 7
	s_and_saveexec_b64 s[30:31], s[8:9]
	s_cbranch_execz .Lq2_first
	v_mov_b32_e32 v251, 1
	global_atomic_add v251, v1, v251, s[20:21] sc0
.Lq2_first:
	s_or_b64 exec, exec, s[30:31]
	s_branch .LBB0_857

.LBB0_857:
	s_setprio 0
	s_barrier
	s_and_saveexec_b64 s[28:29], s[8:9]
	s_cbranch_execz .LBB0_861
	s_waitcnt vmcnt(0)
	v_mov_b32_e32 v2, s71
	ds_write_b32 v2, v251
.LBB0_861:
	s_or_b64 exec, exec, s[28:29]
	v_mov_b32_e32 v0, s71
	s_waitcnt lgkmcnt(0)
	s_barrier
	ds_read_b32 v0, v0
	s_mov_b64 s[6:7], -1
	s_waitcnt lgkmcnt(0)
	v_cmp_le_i32_e32 vcc, s22, v0
	v_readfirstlane_b32 s24, v0
	s_cbranch_vccnz .LBB0_856
	s_and_saveexec_b64 s[30:31], s[8:9]
	s_cbranch_execz .Lq2_nopf
	v_mov_b32_e32 v251, 1
	global_atomic_add v251, v1, v251, s[20:21] sc0
.Lq2_nopf:
	s_or_b64 exec, exec, s[30:31]
	s_cmpk_gt_i32 s24, 0x5f
	s_cbranch_scc0 .LBB0_1256
	s_cmpk_gt_u32 s24, 0x35f
	s_cbranch_scc0 .LBB0_1057
	s_cmpk_gt_u32 s24, 0x95f
	s_cbranch_scc0 .LBB0_1052
	s_cmpk_lt_u32 s24, 0x971
	s_cselect_b32 s25, 0x49b, 0
	s_add_i32 s24, s24, s25
	s_sub_i32 s24, s24, 17
	s_lshl_b32 s25, s24, 3
	s_cmpk_gt_u32 s24, 0xd9b
	s_cbranch_scc0 .LBB0_925
	v_mov_b32_e32 v8, v203
	s_nop 0
	v_readfirstlane_b32 s36, v8
	s_ashr_i32 s10, s36, 6
	s_add_i32 s27, s25, s10
	s_addk_i32 s27, 0x9320
	s_cmpk_gt_i32 s27, 0x2f7
	s_cbranch_scc1 .LBB0_924
	s_mul_i32 s6, s10, 0x2100
	s_add_i32 s26, s6, 0
	v_and_b32_e32 v10, 63, v8
	s_cmp_gt_i32 s27, 47
	s_mov_b64 s[6:7], -1
	s_cbranch_scc0 .LBB0_898
	s_cmpk_gt_u32 s27, 0x5f
	s_cbranch_scc0 .LBB0_895
	s_cmpk_gt_u32 s27, 0x15f
	s_cbranch_scc0 .LBB0_892
	s_cmpk_gt_u32 s27, 0x25f
	s_cbranch_scc0 .LBB0_889
	s_cmpk_gt_u32 s27, 0x267
	s_cbranch_scc0 .LBB0_886
	s_cmpk_gt_u32 s27, 0x26f
	s_cbranch_scc0 .LBB0_883
	s_cmpk_gt_u32 s27, 0x2ef
	s_cbranch_scc0 .LBB0_877
	s_lshl_b32 s6, s24, 9
	s_lshl_b32 s7, s10, 6
	s_add_i32 s6, s6, s7
	s_add_i32 s7, s6, 0xffe40a00
	s_add_i32 s6, s6, 0xffe40c00
	v_or_b32_e32 v0, s7, v10
	v_or_b32_e32 v6, s6, v10
	v_readlane_b32 s6, v248, 5
	v_mov_b32_e32 v2, v1
	v_ashrrev_i32_e32 v7, 31, v6
	v_readlane_b32 s7, v248, 6
	s_mov_b64 s[28:29], 0
	v_mov_b32_e32 v3, v2
	v_mov_b32_e32 v4, v2
	v_mov_b32_e32 v5, v2
	v_lshl_add_u64 v[6:7], v[6:7], 4, s[6:7]
	s_mov_b64 s[10:11], 0x2000

	.amdhsa_kernel _Z4mega4Args
		.amdhsa_group_segment_fixed_size 0
		.amdhsa_private_segment_fixed_size 0
		.amdhsa_kernarg_size 504
		.amdhsa_user_sgpr_count 2
		.amdhsa_user_sgpr_dispatch_ptr 0
		.amdhsa_user_sgpr_queue_ptr 0
		.amdhsa_user_sgpr_kernarg_segment_ptr 1
		.amdhsa_user_sgpr_dispatch_id 0
		.amdhsa_user_sgpr_kernarg_preload_length 0
		.amdhsa_user_sgpr_kernarg_preload_offset 0
		.amdhsa_user_sgpr_private_segment_size 0
		.amdhsa_uses_dynamic_stack 0
		.amdhsa_enable_private_segment 0
		.amdhsa_system_sgpr_workgroup_id_x 1
		.amdhsa_system_sgpr_workgroup_id_y 0
		.amdhsa_system_sgpr_workgroup_id_z 0
		.amdhsa_system_sgpr_workgroup_info 0
		.amdhsa_system_vgpr_workitem_id 2
		.amdhsa_next_free_vgpr 252
		.amdhsa_next_free_sgpr 100
		.amdhsa_accum_offset 252
		.amdhsa_reserve_vcc 1
		.amdhsa_float_round_mode_32 0
		.amdhsa_float_round_mode_16_64 0
		.amdhsa_float_denorm_mode_32 3
		.amdhsa_float_denorm_mode_16_64 3
		.amdhsa_dx10_clamp 1
		.amdhsa_ieee_mode 1
		.amdhsa_fp16_overflow 0
		.amdhsa_tg_split 0
		.amdhsa_exception_fp_ieee_invalid_op 0
		.amdhsa_exception_fp_denorm_src 0
		.amdhsa_exception_fp_ieee_div_zero 0
		.amdhsa_exception_fp_ieee_overflow 0
		.amdhsa_exception_fp_ieee_underflow 0
		.amdhsa_exception_fp_ieee_inexact 0
		.amdhsa_exception_int_div_zero 0
	.end_amdhsa_kernel

amdhsa.kernels:
  - .agpr_count:     0
    .args:
      - .offset:         0
        .size:           248
        .value_kind:     by_value
      - .offset:         248
        .size:           4
        .value_kind:     hidden_block_count_x
      - .offset:         252
        .size:           4
        .value_kind:     hidden_block_count_y
      - .offset:         256
        .size:           4
        .value_kind:     hidden_block_count_z
      - .offset:         260
        .size:           2
        .value_kind:     hidden_group_size_x
      - .offset:         262
        .size:           2
        .value_kind:     hidden_group_size_y
      - .offset:         264
        .size:           2
        .value_kind:     hidden_group_size_z
      - .offset:         266
        .size:           2
        .value_kind:     hidden_remainder_x
      - .offset:         268
        .size:           2
        .value_kind:     hidden_remainder_y
      - .offset:         270
        .size:           2
        .value_kind:     hidden_remainder_z
      - .offset:         288
        .size:           8
        .value_kind:     hidden_global_offset_x
      - .offset:         296
        .size:           8
        .value_kind:     hidden_global_offset_y
      - .offset:         304
        .size:           8
        .value_kind:     hidden_global_offset_z
      - .offset:         312
        .size:           2
        .value_kind:     hidden_grid_dims
      - .offset:         336
        .size:           8
        .value_kind:     hidden_multigrid_sync_arg
      - .offset:         368
        .size:           4
        .value_kind:     hidden_dynamic_lds_size
    .group_segment_fixed_size: 0
    .kernarg_segment_align: 8
    .kernarg_segment_size: 504
    .language:       OpenCL C
    .language_version:
      - 2
      - 0
    .max_flat_workgroup_size: 512
    .name:           _Z4mega4Args
    .private_segment_fixed_size: 0
    .sgpr_count:     106
    .sgpr_spill_count: 164
    .symbol:         _Z4mega4Args.kd
    .uniform_work_group_size: 1
    .uses_dynamic_stack: false
    .vgpr_count:     252
    .vgpr_spill_count: 0
    .wavefront_size: 64
